# r48 + every 8-byte instruction of the M4 merge phase made 8-byte aligned with s_nop 0 fillers (203), later code parity preserved
# baseline (speedup 1.0000x reference)
.LBB0_1173:
	s_nop 0
	s_mul_hi_u32 s12, s35, 0xaaaaaaab
	s_lshr_b32 s16, s12, 1
	s_nop 0
	s_mul_i32 s16, s16, 0x24000
	v_subrev_u32_e32 v114, s16, v152
	v_subrev_u32_e32 v115, s16, v153
	v_add_u32_e32 v139, s29, v141
	s_waitcnt lgkmcnt(7)
	v_mfma_f32_16x16x32_bf16 v[110:113], v[18:21], v[2:5], v[110:113]
	v_add_u32_e32 v115, v139, v115
	v_add_u32_e32 v114, v139, v114
	ds_read_b128 v[122:125], v115 offset:16384
	ds_read_b128 v[118:121], v115 offset:18432
	ds_read_b128 v[126:129], v114 offset:16384
	ds_read_b128 v[114:117], v114 offset:18432
	s_waitcnt lgkmcnt(9)
	s_nop 0
	v_mfma_f32_16x16x32_bf16 v[106:109], v[26:29], v[2:5], v[106:109]
	s_cmp_ge_i32 s21, s17
	s_cselect_b64 s[12:13], -1, 0
	s_or_b64 s[12:13], s[14:15], s[12:13]
	s_waitcnt lgkmcnt(7)
	v_mfma_f32_16x16x32_bf16 v[102:105], v[34:37], v[2:5], v[102:105]
	s_and_b64 vcc, exec, s[12:13]
	s_mov_b64 s[12:13], -1
	s_waitcnt lgkmcnt(6)
	s_nop 0
	v_mfma_f32_16x16x32_bf16 v[98:101], v[38:41], v[2:5], v[98:101]
	v_mfma_f32_16x16x32_bf16 v[94:97], v[18:21], v[6:9], v[94:97]
	v_mfma_f32_16x16x32_bf16 v[90:93], v[26:29], v[6:9], v[90:93]
	v_mfma_f32_16x16x32_bf16 v[86:89], v[34:37], v[6:9], v[86:89]
	v_mfma_f32_16x16x32_bf16 v[82:85], v[38:41], v[6:9], v[82:85]
	v_mfma_f32_16x16x32_bf16 v[110:113], v[22:25], v[10:13], v[110:113]
	v_mfma_f32_16x16x32_bf16 v[106:109], v[30:33], v[10:13], v[106:109]
	s_waitcnt lgkmcnt(5)
	s_nop 0
	v_mfma_f32_16x16x32_bf16 v[102:105], v[42:45], v[10:13], v[102:105]
	s_waitcnt lgkmcnt(4)
	s_nop 0
	v_mfma_f32_16x16x32_bf16 v[98:101], v[46:49], v[10:13], v[98:101]
	v_mfma_f32_16x16x32_bf16 v[94:97], v[22:25], v[14:17], v[94:97]
	v_mfma_f32_16x16x32_bf16 v[90:93], v[30:33], v[14:17], v[90:93]
	v_mfma_f32_16x16x32_bf16 v[86:89], v[42:45], v[14:17], v[86:89]
	v_mfma_f32_16x16x32_bf16 v[82:85], v[46:49], v[14:17], v[82:85]
	s_cbranch_vccnz .LBB0_1175
	s_waitcnt vmcnt(6)
	s_mov_b64 s[12:13], 0

.LBB0_1177:
	s_waitcnt lgkmcnt(0)
	s_andn2_b64 vcc, exec, s[10:11]
	s_barrier
	s_cbranch_vccnz .LBB0_1185
	s_sub_i32 s10, s19, s16
	s_sub_i32 s11, s24, s16
	s_add_i32 s10, s29, s10
	s_nop 0
	v_lshl_add_u64 v[238:239], s[8:9], 0, v[130:131]
	s_add_i32 m0, s10, 0
	s_add_i32 s10, s29, s11
	s_sub_i32 s12, s25, s16
	s_sub_i32 s13, s26, s16
	s_sub_i32 s14, s27, s16
	s_sub_i32 s15, s28, s16
	global_load_lds_dwordx4 v[238:239], off
	s_add_i32 m0, s10, 0
	s_nop 0
	s_add_u32 s10, s8, 0x40000
	v_lshl_add_u64 v[238:239], s[8:9], 0, v[132:133]
	s_addc_u32 s11, s9, 0
	s_add_i32 s13, s29, s13
	global_load_lds_dwordx4 v[238:239], off
	v_lshl_add_u64 v[238:239], s[10:11], 0, v[130:131]
	s_add_i32 m0, s13, 0
	s_nop 0
	v_cndmask_b32_e64 v240, v132, v134, s[4:5]
	global_load_lds_dwordx4 v[238:239], off
	v_lshl_add_u64 v[238:239], s[10:11], 0, v[132:133]
	s_add_i32 s10, s29, s15
	s_add_i32 m0, s10, 0
	s_add_i32 s10, s29, s12
	s_nop 0
	global_load_lds_dwordx4 v[238:239], off
	v_cndmask_b32_e64 v238, v130, v136, s[4:5]
	v_mov_b32_e32 v239, v0
	s_add_i32 m0, s10, 0
	v_mov_b32_e32 v241, v0
	s_nop 0
	v_lshl_add_u64 v[238:239], s[0:1], 0, v[238:239]
	s_add_i32 s10, s29, s14
	s_nop 0
	global_load_lds_dwordx4 v[238:239], off
	v_lshl_add_u64 v[238:239], s[0:1], 0, v[240:241]
	s_add_i32 m0, s10, 0
	s_add_i32 s30, s30, 1
	global_load_lds_dwordx4 v[238:239], off
	s_add_u32 s8, s8, 0x80
	s_addc_u32 s9, s9, 0
	s_nop 0
	s_add_u32 s0, s0, 0x80
	s_addc_u32 s1, s1, 0
	s_cmp_lg_u32 s30, s34
	s_mov_b64 s[10:11], -1
	s_cbranch_scc1 .LBB0_1193
	s_cmp_lg_u32 s44, 1
	s_cselect_b64 s[12:13], -1, 0
	s_mov_b32 s45, 1
	s_mov_b64 s[14:15], -1
	s_and_b64 vcc, exec, s[12:13]
	s_cbranch_vccnz .LBB0_1186
	v_readlane_b32 s2, v252, 28
	v_readlane_b32 s3, v252, 29
	s_add_i32 s16, s43, 1
	s_and_b64 vcc, exec, s[2:3]
	s_cbranch_vccz .LBB0_1182
	s_mul_i32 s10, s16, s76
	s_add_i32 s31, s10, s73
	s_mov_b64 s[10:11], 0
.LBB0_1182:
	s_andn2_b64 vcc, exec, s[10:11]
	s_cbranch_vccnz .LBB0_1184
	s_lshl_b32 s10, s16, 8
	s_nop 0
	v_readlane_b32 s2, v252, 30
	s_add_i32 s10, s2, s10
	s_cmp_lt_i32 s43, 3
	s_cselect_b32 s31, s10, 0x400

.LBB0_1187:
	s_ashr_i32 s0, s31, 3
	s_ashr_i32 s1, s0, 31
	s_and_b32 s14, s31, 7
	s_lshl_b64 s[10:11], s[0:1], 19
	s_mov_b64 s[4:5], -1
	s_and_b64 vcc, exec, s[12:13]
	s_mov_b64 s[12:13], -1
	s_cbranch_vccz .LBB0_1189
	v_readlane_b32 s52, v253, 32
	v_readlane_b32 s58, v253, 38
	v_readlane_b32 s59, v253, 39
	s_add_u32 s0, s58, s10
	s_addc_u32 s1, s59, s11
	s_add_u32 s8, s0, 0x400
	v_readlane_b32 s53, v253, 33
	v_readlane_b32 s54, v253, 34
	v_readlane_b32 s55, v253, 35
	v_readlane_b32 s56, v253, 36
	v_readlane_b32 s57, v253, 37
	v_readlane_b32 s60, v253, 40
	v_readlane_b32 s61, v253, 41
	v_readlane_b32 s62, v253, 42
	v_readlane_b32 s63, v253, 43
	v_readlane_b32 s64, v253, 44
	v_readlane_b32 s65, v253, 45
	v_readlane_b32 s66, v253, 46
	v_readlane_b32 s67, v253, 47
	s_addc_u32 s9, s1, 0
	s_lshl_b32 s0, s14, 7
	s_or_b32 s0, s68, s0
	s_mov_b32 s1, s69
	v_readlane_b32 s52, v251, 16
	s_lshl_b64 s[0:1], s[0:1], 9
	s_nop 0
	v_readlane_b32 s62, v251, 26
	v_readlane_b32 s63, v251, 27
	s_add_u32 s0, s62, s0
	s_addc_u32 s1, s63, s1
	s_add_u32 s0, s0, 0x100000
	v_readlane_b32 s53, v251, 17
	v_readlane_b32 s54, v251, 18
	v_readlane_b32 s55, v251, 19
	v_readlane_b32 s56, v251, 20
	v_readlane_b32 s57, v251, 21
	v_readlane_b32 s58, v251, 22
	v_readlane_b32 s59, v251, 23
	v_readlane_b32 s60, v251, 24
	v_readlane_b32 s61, v251, 25
	v_readlane_b32 s64, v251, 28
	v_readlane_b32 s65, v251, 29
	v_readlane_b32 s66, v251, 30
	v_readlane_b32 s67, v251, 31
	s_addc_u32 s1, s1, 0
	s_mov_b64 s[12:13], 0
.LBB0_1189:
	s_andn2_b64 vcc, exec, s[12:13]
	s_mov_b32 s40, 4
	s_cbranch_vccnz .LBB0_1191
	s_nop 0
	v_readlane_b32 s52, v251, 16
	v_readlane_b32 s66, v251, 30
	v_readlane_b32 s67, v251, 31
	s_add_u32 s8, s66, s10
	s_addc_u32 s9, s67, s11
	s_lshl_b32 s0, s14, 7
	s_addk_i32 s0, 0xf80
	s_add_u32 s0, s48, s0
	s_addc_u32 s1, 0, 0
	v_readlane_b32 s60, v251, 24
	s_lshl_b64 s[0:1], s[0:1], 11
	s_nop 0
	v_readlane_b32 s61, v251, 25
	s_add_u32 s0, s60, s0
	s_addc_u32 s1, s61, s1
	s_add_u32 s0, s0, 0x400000
	s_addc_u32 s1, s1, 0
	s_mov_b32 s40, 16
	s_mov_b64 s[4:5], 0
	s_nop 0
	v_readlane_b32 s53, v251, 17
	v_readlane_b32 s54, v251, 18
	v_readlane_b32 s55, v251, 19
	v_readlane_b32 s56, v251, 20
	v_readlane_b32 s57, v251, 21
	v_readlane_b32 s58, v251, 22
	v_readlane_b32 s59, v251, 23
	v_readlane_b32 s62, v251, 26
	v_readlane_b32 s63, v251, 27
	v_readlane_b32 s64, v251, 28
	v_readlane_b32 s65, v251, 29

.LBB0_1194:
	s_mul_hi_u32 s12, s20, 0xaaaaaaab
	s_lshr_b32 s14, s12, 1
	s_add_i32 s16, s21, -1
	s_cmp_lt_i32 s16, s17
	s_cselect_b64 s[12:13], -1, 0
	s_cmp_ge_i32 s16, s17
	s_nop 0
	s_mul_i32 s14, s14, 0x24000
	s_cbranch_scc1 .LBB0_1196
	v_subrev_u32_e32 v2, s14, v142
	v_subrev_u32_e32 v3, s14, v143
	v_subrev_u32_e32 v4, s14, v144
	v_subrev_u32_e32 v5, s14, v145
	v_add_u32_e32 v2, v139, v2
	v_add_u32_e32 v6, v139, v3
	v_add_u32_e32 v10, v139, v4
	v_add_u32_e32 v14, v139, v5
	s_nop 0
	ds_read_b128 v[2:5], v2
	ds_read_b128 v[6:9], v6
	ds_read_b128 v[10:13], v10
	ds_read_b128 v[14:17], v14
.LBB0_1196:
	v_mfma_f32_16x16x32_bf16 v[78:81], v[18:21], v[122:125], v[78:81]
	s_andn2_b64 vcc, exec, s[12:13]
	s_nop 0
	v_mfma_f32_16x16x32_bf16 v[74:77], v[26:29], v[122:125], v[74:77]
	v_mfma_f32_16x16x32_bf16 v[70:73], v[34:37], v[122:125], v[70:73]
	v_mfma_f32_16x16x32_bf16 v[66:69], v[38:41], v[122:125], v[66:69]
	v_mfma_f32_16x16x32_bf16 v[62:65], v[18:21], v[118:121], v[62:65]
	v_mfma_f32_16x16x32_bf16 v[58:61], v[26:29], v[118:121], v[58:61]
	v_mfma_f32_16x16x32_bf16 v[54:57], v[34:37], v[118:121], v[54:57]
	v_mfma_f32_16x16x32_bf16 v[50:53], v[38:41], v[118:121], v[50:53]
	v_mfma_f32_16x16x32_bf16 v[78:81], v[22:25], v[126:129], v[78:81]
	v_mfma_f32_16x16x32_bf16 v[74:77], v[30:33], v[126:129], v[74:77]
	v_mfma_f32_16x16x32_bf16 v[70:73], v[42:45], v[126:129], v[70:73]
	v_mfma_f32_16x16x32_bf16 v[66:69], v[46:49], v[126:129], v[66:69]
	v_mfma_f32_16x16x32_bf16 v[62:65], v[22:25], v[114:117], v[62:65]
	v_mfma_f32_16x16x32_bf16 v[58:61], v[30:33], v[114:117], v[58:61]
	v_mfma_f32_16x16x32_bf16 v[54:57], v[42:45], v[114:117], v[54:57]
	v_mfma_f32_16x16x32_bf16 v[50:53], v[46:49], v[114:117], v[50:53]
	s_cbranch_vccnz .LBB0_1198
	v_subrev_u32_e32 v26, s14, v146
	v_subrev_u32_e32 v34, s14, v147
	v_subrev_u32_e32 v18, s14, v148
	v_subrev_u32_e32 v27, s14, v149
	v_subrev_u32_e32 v35, s14, v150
	v_subrev_u32_e32 v19, s14, v151
	v_add_u32_e32 v19, v139, v19
	v_add_u32_e32 v22, v139, v18
	v_add_u32_e32 v27, v139, v27
	v_add_u32_e32 v30, v139, v26
	v_add_u32_e32 v38, v139, v35
	v_add_u32_e32 v46, v139, v34
	s_nop 0
	ds_read_b128 v[18:21], v19
	ds_read_b128 v[22:25], v22
	ds_read_b128 v[26:29], v27
	ds_read_b128 v[30:33], v30
	ds_read_b128 v[34:37], v38
	ds_read_b128 v[38:41], v38 offset:2048
	ds_read_b128 v[42:45], v46
	ds_read_b128 v[46:49], v46 offset:2048
.LBB0_1198:
	s_add_i32 s36, s36, 1
	s_cmp_eq_u32 s36, s37
	s_cselect_b64 s[12:13], -1, 0
	s_cmp_lg_u32 s36, s37
	s_cbranch_scc1 .LBB0_1204
	s_xor_b64 s[14:15], s[6:7], -1
	s_andn2_b64 vcc, exec, s[14:15]
	s_mov_b64 s[14:15], -1
	s_cbranch_vccnz .LBB0_1201
	s_nop 0
	ds_read2_b32 v[114:115], v137 offset1:16
	s_mov_b64 s[14:15], 0
	s_waitcnt lgkmcnt(0)
	v_pk_mul_f32 v[116:117], v[110:111], v[114:115] op_sel_hi:[1,0]
	s_nop 0
	s_nop 0
	v_mul_f32_e32 v116, 0xbfb8aa3b, v116
	v_mul_f32_e32 v117, 0xbfb8aa3b, v117
	v_exp_f32_e32 v116, v116
	v_exp_f32_e32 v117, v117
	v_pk_mul_f32 v[118:119], v[112:113], v[114:115] op_sel_hi:[1,0]
	v_pk_mul_f32 v[120:121], v[108:109], v[114:115] op_sel_hi:[1,0]
	v_add_f32_e32 v116, 1.0, v116
	v_add_f32_e32 v117, 1.0, v117
	v_rcp_f32_e32 v116, v116
	v_rcp_f32_e32 v117, v117
	v_pk_mul_f32 v[122:123], v[104:105], v[114:115] op_sel_hi:[1,0]
	v_pk_mul_f32 v[124:125], v[100:101], v[114:115] op_sel_hi:[1,0]
	v_cvt_pk_bf16_f32 v116, v116, v117
	v_mul_f32_e32 v117, 0xbfb8aa3b, v118
	v_mul_f32_e32 v118, 0xbfb8aa3b, v119
	v_exp_f32_e32 v117, v117
	v_exp_f32_e32 v118, v118
	v_add_f32_e32 v117, 1.0, v117
	v_add_f32_e32 v118, 1.0, v118
	v_rcp_f32_e32 v117, v117
	v_rcp_f32_e32 v118, v118
	s_nop 0
	s_nop 0
	v_cvt_pk_bf16_f32 v117, v117, v118
	v_pk_mul_f32 v[118:119], v[106:107], v[114:115] op_sel_hi:[1,0]
	s_nop 0
	s_nop 0
	v_mul_f32_e32 v118, 0xbfb8aa3b, v118
	v_mul_f32_e32 v119, 0xbfb8aa3b, v119
	v_exp_f32_e32 v118, v118
	v_exp_f32_e32 v119, v119
	v_add_f32_e32 v118, 1.0, v118
	v_add_f32_e32 v119, 1.0, v119
	v_rcp_f32_e32 v118, v118
	v_rcp_f32_e32 v119, v119
	s_nop 0
	s_nop 0
	v_cvt_pk_bf16_f32 v118, v118, v119
	v_mul_f32_e32 v119, 0xbfb8aa3b, v120
	v_mul_f32_e32 v120, 0xbfb8aa3b, v121
	v_exp_f32_e32 v119, v119
	v_exp_f32_e32 v120, v120
	v_add_f32_e32 v119, 1.0, v119
	v_add_f32_e32 v120, 1.0, v120
	v_rcp_f32_e32 v119, v119
	v_rcp_f32_e32 v120, v120
	s_nop 0
	s_nop 0
	v_cvt_pk_bf16_f32 v119, v119, v120
	v_pk_mul_f32 v[120:121], v[102:103], v[114:115] op_sel_hi:[1,0]
	s_nop 0
	s_nop 0
	v_mul_f32_e32 v120, 0xbfb8aa3b, v120
	v_mul_f32_e32 v121, 0xbfb8aa3b, v121
	v_exp_f32_e32 v120, v120
	v_exp_f32_e32 v121, v121
	v_add_f32_e32 v120, 1.0, v120
	v_add_f32_e32 v121, 1.0, v121
	v_rcp_f32_e32 v120, v120
	v_rcp_f32_e32 v121, v121
	s_nop 0
	s_nop 0
	v_cvt_pk_bf16_f32 v120, v120, v121
	v_mul_f32_e32 v121, 0xbfb8aa3b, v122
	v_mul_f32_e32 v122, 0xbfb8aa3b, v123
	v_exp_f32_e32 v121, v121
	v_exp_f32_e32 v122, v122
	v_add_f32_e32 v121, 1.0, v121
	v_add_f32_e32 v122, 1.0, v122
	v_rcp_f32_e32 v121, v121
	v_rcp_f32_e32 v122, v122
	s_nop 0
	s_nop 0
	v_cvt_pk_bf16_f32 v121, v121, v122
	v_pk_mul_f32 v[122:123], v[98:99], v[114:115] op_sel_hi:[1,0]
	s_nop 0
	s_nop 0
	v_mul_f32_e32 v114, 0xbfb8aa3b, v122
	v_mul_f32_e32 v122, 0xbfb8aa3b, v123
	v_exp_f32_e32 v114, v114
	v_exp_f32_e32 v122, v122
	v_mul_f32_e32 v123, 0xbfb8aa3b, v125
	v_exp_f32_e32 v123, v123
	v_add_f32_e32 v114, 1.0, v114
	v_add_f32_e32 v122, 1.0, v122
	v_rcp_f32_e32 v114, v114
	v_rcp_f32_e32 v122, v122
	v_add_f32_e32 v123, 1.0, v123
	v_rcp_f32_e32 v123, v123
	s_nop 0
	v_cvt_pk_bf16_f32 v122, v114, v122
	v_mul_f32_e32 v114, 0xbfb8aa3b, v124
	v_exp_f32_e32 v114, v114
	s_nop 0
	v_add_f32_e32 v114, 1.0, v114
	v_rcp_f32_e32 v114, v114
	s_nop 0
	s_nop 0
	v_cvt_pk_bf16_f32 v123, v114, v123
	v_mov_b32_e32 v114, v115
	s_nop 0
	v_pk_mul_f32 v[124:125], v[94:95], v[114:115] op_sel_hi:[1,0]
	v_pk_mul_f32 v[126:127], v[96:97], v[114:115] op_sel_hi:[1,0]
	v_mul_f32_e32 v115, 0xbfb8aa3b, v124
	v_mul_f32_e32 v124, 0xbfb8aa3b, v125
	v_exp_f32_e32 v115, v115
	v_exp_f32_e32 v124, v124
	v_mul_f32_e32 v125, 0xbfb8aa3b, v127
	v_exp_f32_e32 v125, v125
	v_add_f32_e32 v115, 1.0, v115
	v_add_f32_e32 v124, 1.0, v124
	v_rcp_f32_e32 v115, v115
	v_rcp_f32_e32 v124, v124
	v_add_f32_e32 v125, 1.0, v125
	v_rcp_f32_e32 v125, v125
	s_nop 0
	v_cvt_pk_bf16_f32 v124, v115, v124
	v_mul_f32_e32 v115, 0xbfb8aa3b, v126
	v_exp_f32_e32 v115, v115
	s_nop 0
	v_add_f32_e32 v115, 1.0, v115
	v_rcp_f32_e32 v115, v115
	s_nop 0
	s_nop 0
	v_pk_mul_f32 v[126:127], v[90:91], v[114:115] op_sel_hi:[1,0]
	v_cvt_pk_bf16_f32 v125, v115, v125
	v_pk_mul_f32 v[128:129], v[92:93], v[114:115] op_sel_hi:[1,0]
	v_mul_f32_e32 v115, 0xbfb8aa3b, v126
	v_mul_f32_e32 v126, 0xbfb8aa3b, v127
	v_exp_f32_e32 v115, v115
	v_exp_f32_e32 v126, v126
	v_mul_f32_e32 v127, 0xbfb8aa3b, v129
	v_exp_f32_e32 v127, v127
	v_add_f32_e32 v115, 1.0, v115
	v_add_f32_e32 v126, 1.0, v126
	v_rcp_f32_e32 v115, v115
	v_rcp_f32_e32 v126, v126
	v_add_f32_e32 v127, 1.0, v127
	v_rcp_f32_e32 v127, v127
	s_nop 0
	v_cvt_pk_bf16_f32 v126, v115, v126
	v_mul_f32_e32 v115, 0xbfb8aa3b, v128
	v_exp_f32_e32 v115, v115
	s_nop 0
	v_add_f32_e32 v115, 1.0, v115
	v_rcp_f32_e32 v115, v115
	s_nop 0
	s_nop 0
	v_pk_mul_f32 v[128:129], v[86:87], v[114:115] op_sel_hi:[1,0]
	v_cvt_pk_bf16_f32 v127, v115, v127
	v_pk_mul_f32 v[238:239], v[88:89], v[114:115] op_sel_hi:[1,0]
	v_mul_f32_e32 v115, 0xbfb8aa3b, v128
	v_mul_f32_e32 v128, 0xbfb8aa3b, v129
	v_exp_f32_e32 v115, v115
	v_exp_f32_e32 v128, v128
	v_mul_f32_e32 v129, 0xbfb8aa3b, v239
	v_exp_f32_e32 v129, v129
	v_add_f32_e32 v115, 1.0, v115
	v_add_f32_e32 v128, 1.0, v128
	v_rcp_f32_e32 v115, v115
	v_rcp_f32_e32 v128, v128
	v_add_f32_e32 v129, 1.0, v129
	v_rcp_f32_e32 v129, v129
	s_nop 0
	v_cvt_pk_bf16_f32 v128, v115, v128
	v_mul_f32_e32 v115, 0xbfb8aa3b, v238
	v_exp_f32_e32 v115, v115
	s_nop 0
	v_add_f32_e32 v115, 1.0, v115
	v_rcp_f32_e32 v115, v115
	s_nop 0
	s_nop 0
	v_cvt_pk_bf16_f32 v129, v115, v129
	v_pk_mul_f32 v[238:239], v[84:85], v[114:115] op_sel_hi:[1,0]
	v_pk_mul_f32 v[114:115], v[82:83], v[114:115] op_sel_hi:[1,0]
	s_nop 0
	s_nop 0
	v_mul_f32_e32 v114, 0xbfb8aa3b, v114
	v_mul_f32_e32 v115, 0xbfb8aa3b, v115
	v_exp_f32_e32 v114, v114
	v_exp_f32_e32 v115, v115
	v_add_f32_e32 v114, 1.0, v114
	v_add_f32_e32 v115, 1.0, v115
	v_rcp_f32_e32 v114, v114
	v_rcp_f32_e32 v115, v115
	s_nop 0
	s_nop 0
	v_cvt_pk_bf16_f32 v139, v114, v115
	v_mul_f32_e32 v114, 0xbfb8aa3b, v238
	v_mul_f32_e32 v115, 0xbfb8aa3b, v239
	v_exp_f32_e32 v114, v114
	v_exp_f32_e32 v115, v115
	v_add_f32_e32 v114, 1.0, v114
	v_add_f32_e32 v115, 1.0, v115
	v_rcp_f32_e32 v114, v114
	v_rcp_f32_e32 v115, v115
	s_nop 0
	s_nop 0
	v_cvt_pk_bf16_f32 v237, v114, v115
	ds_read2_b32 v[114:115], v137 offset0:128 offset1:144
	s_waitcnt lgkmcnt(0)
	s_nop 0
	v_pk_mul_f32 v[238:239], v[78:79], v[114:115] op_sel_hi:[1,0]
	s_nop 0
	s_nop 0
	v_mul_f32_e32 v155, 0xbfb8aa3b, v238
	v_mul_f32_e32 v186, 0xbfb8aa3b, v239
	v_exp_f32_e32 v155, v155
	v_exp_f32_e32 v186, v186
	v_pk_mul_f32 v[240:241], v[80:81], v[114:115] op_sel_hi:[1,0]
	v_pk_mul_f32 v[242:243], v[76:77], v[114:115] op_sel_hi:[1,0]
	v_add_f32_e32 v155, 1.0, v155
	v_add_f32_e32 v186, 1.0, v186
	v_rcp_f32_e32 v155, v155
	v_rcp_f32_e32 v186, v186
	v_pk_mul_f32 v[244:245], v[72:73], v[114:115] op_sel_hi:[1,0]
	v_pk_mul_f32 v[246:247], v[66:67], v[114:115] op_sel_hi:[1,0]
	v_cvt_pk_bf16_f32 v238, v155, v186
	v_mul_f32_e32 v155, 0xbfb8aa3b, v240
	v_mul_f32_e32 v186, 0xbfb8aa3b, v241
	v_exp_f32_e32 v155, v155
	v_exp_f32_e32 v186, v186
	v_pk_mul_f32 v[240:241], v[74:75], v[114:115] op_sel_hi:[1,0]
	v_add_f32_e32 v155, 1.0, v155
	v_add_f32_e32 v186, 1.0, v186
	v_rcp_f32_e32 v155, v155
	v_rcp_f32_e32 v186, v186
	s_nop 0
	s_nop 0
	v_cvt_pk_bf16_f32 v239, v155, v186
	v_mul_f32_e32 v155, 0xbfb8aa3b, v240
	v_mul_f32_e32 v186, 0xbfb8aa3b, v241
	v_exp_f32_e32 v155, v155
	v_exp_f32_e32 v186, v186
	v_add_f32_e32 v155, 1.0, v155
	v_add_f32_e32 v186, 1.0, v186
	v_rcp_f32_e32 v155, v155
	v_rcp_f32_e32 v186, v186
	s_nop 0
	s_nop 0
	v_cvt_pk_bf16_f32 v240, v155, v186
	v_mul_f32_e32 v155, 0xbfb8aa3b, v242
	v_mul_f32_e32 v186, 0xbfb8aa3b, v243
	v_exp_f32_e32 v155, v155
	v_exp_f32_e32 v186, v186
	v_pk_mul_f32 v[242:243], v[70:71], v[114:115] op_sel_hi:[1,0]
	v_add_f32_e32 v155, 1.0, v155
	v_add_f32_e32 v186, 1.0, v186
	v_rcp_f32_e32 v155, v155
	v_rcp_f32_e32 v186, v186
	s_nop 0
	s_nop 0
	v_cvt_pk_bf16_f32 v241, v155, v186
	v_mul_f32_e32 v155, 0xbfb8aa3b, v242
	v_mul_f32_e32 v186, 0xbfb8aa3b, v243
	v_exp_f32_e32 v155, v155
	v_exp_f32_e32 v186, v186
	v_add_f32_e32 v155, 1.0, v155
	v_add_f32_e32 v186, 1.0, v186
	v_rcp_f32_e32 v155, v155
	v_rcp_f32_e32 v186, v186
	s_nop 0
	s_nop 0
	v_cvt_pk_bf16_f32 v242, v155, v186
	v_mul_f32_e32 v155, 0xbfb8aa3b, v244
	v_mul_f32_e32 v186, 0xbfb8aa3b, v245
	v_exp_f32_e32 v155, v155
	v_exp_f32_e32 v186, v186
	v_pk_mul_f32 v[244:245], v[68:69], v[114:115] op_sel_hi:[1,0]
	v_mul_f32_e32 v114, 0xbfb8aa3b, v246
	v_add_f32_e32 v155, 1.0, v155
	v_add_f32_e32 v186, 1.0, v186
	v_rcp_f32_e32 v155, v155
	v_rcp_f32_e32 v186, v186
	v_exp_f32_e32 v114, v114
	s_nop 0
	v_cvt_pk_bf16_f32 v243, v155, v186
	v_mul_f32_e32 v155, 0xbfb8aa3b, v247
	v_exp_f32_e32 v155, v155
	v_add_f32_e32 v114, 1.0, v114
	v_rcp_f32_e32 v114, v114
	s_nop 0
	v_mul_f32_e32 v186, 0xbfb8aa3b, v245
	v_add_f32_e32 v155, 1.0, v155
	v_rcp_f32_e32 v155, v155
	v_exp_f32_e32 v186, v186
	s_nop 0
	v_cvt_pk_bf16_f32 v114, v114, v155
	v_mul_f32_e32 v155, 0xbfb8aa3b, v244
	v_exp_f32_e32 v155, v155
	v_add_f32_e32 v186, 1.0, v186
	v_rcp_f32_e32 v186, v186
	v_add_f32_e32 v155, 1.0, v155
	v_rcp_f32_e32 v155, v155
	s_nop 0
	v_cvt_pk_bf16_f32 v244, v155, v186
	v_mov_b32_e32 v186, v115
	s_nop 0
	v_pk_mul_f32 v[248:249], v[62:63], v[186:187] op_sel_hi:[1,0]
	v_pk_mul_f32 v[246:247], v[64:65], v[186:187] op_sel_hi:[1,0]
	v_mul_f32_e32 v115, 0xbfb8aa3b, v248
	v_mul_f32_e32 v155, 0xbfb8aa3b, v249
	v_exp_f32_e32 v115, v115
	v_exp_f32_e32 v155, v155
	v_mul_f32_e32 v187, 0xbfb8aa3b, v247
	v_exp_f32_e32 v187, v187
	v_add_f32_e32 v115, 1.0, v115
	v_add_f32_e32 v155, 1.0, v155
	v_rcp_f32_e32 v115, v115
	v_rcp_f32_e32 v155, v155
	v_add_f32_e32 v187, 1.0, v187
	v_rcp_f32_e32 v187, v187
	s_nop 0
	v_cvt_pk_bf16_f32 v115, v115, v155
	v_mul_f32_e32 v155, 0xbfb8aa3b, v246
	v_exp_f32_e32 v155, v155
	s_nop 0
	v_pk_mul_f32 v[246:247], v[58:59], v[186:187] op_sel_hi:[1,0]
	v_pk_mul_f32 v[248:249], v[60:61], v[186:187] op_sel_hi:[1,0]
	v_add_f32_e32 v155, 1.0, v155
	v_rcp_f32_e32 v155, v155
	s_nop 0
	s_nop 0
	v_cvt_pk_bf16_f32 v245, v155, v187
	v_mul_f32_e32 v155, 0xbfb8aa3b, v246
	v_mul_f32_e32 v187, 0xbfb8aa3b, v247
	v_exp_f32_e32 v155, v155
	v_exp_f32_e32 v187, v187
	v_add_f32_e32 v155, 1.0, v155
	v_add_f32_e32 v187, 1.0, v187
	v_rcp_f32_e32 v155, v155
	v_rcp_f32_e32 v187, v187
	s_nop 0
	s_nop 0
	v_cvt_pk_bf16_f32 v246, v155, v187
	v_mul_f32_e32 v187, 0xbfb8aa3b, v249
	v_mul_f32_e32 v155, 0xbfb8aa3b, v248
	v_exp_f32_e32 v187, v187
	v_exp_f32_e32 v155, v155
	v_add_f32_e32 v187, 1.0, v187
	v_add_f32_e32 v155, 1.0, v155
	v_rcp_f32_e32 v187, v187
	v_rcp_f32_e32 v155, v155
	v_pk_mul_f32 v[248:249], v[54:55], v[186:187] op_sel_hi:[1,0]
	v_cvt_pk_bf16_f32 v247, v155, v187
	v_pk_mul_f32 v[192:193], v[56:57], v[186:187] op_sel_hi:[1,0]
	v_mul_f32_e32 v155, 0xbfb8aa3b, v248
	v_mul_f32_e32 v187, 0xbfb8aa3b, v249
	v_exp_f32_e32 v155, v155
	v_exp_f32_e32 v187, v187
	v_add_f32_e32 v155, 1.0, v155
	v_add_f32_e32 v187, 1.0, v187
	v_rcp_f32_e32 v155, v155
	v_rcp_f32_e32 v187, v187
	s_nop 0
	s_nop 0
	v_cvt_pk_bf16_f32 v248, v155, v187
	v_mul_f32_e32 v155, 0xbfb8aa3b, v192
	v_mul_f32_e32 v187, 0xbfb8aa3b, v193
	v_exp_f32_e32 v155, v155
	v_exp_f32_e32 v187, v187
	v_add_f32_e32 v155, 1.0, v155
	v_add_f32_e32 v187, 1.0, v187
	v_rcp_f32_e32 v155, v155
	v_rcp_f32_e32 v187, v187
	s_nop 0
	s_nop 0
	v_cvt_pk_bf16_f32 v249, v155, v187
	v_pk_mul_f32 v[192:193], v[52:53], v[186:187] op_sel_hi:[1,0]
	v_pk_mul_f32 v[186:187], v[50:51], v[186:187] op_sel_hi:[1,0]
	s_nop 0
	s_nop 0
	v_mul_f32_e32 v155, 0xbfb8aa3b, v186
	v_mul_f32_e32 v186, 0xbfb8aa3b, v187
	v_exp_f32_e32 v155, v155
	v_exp_f32_e32 v186, v186
	v_add_f32_e32 v155, 1.0, v155
	v_add_f32_e32 v186, 1.0, v186
	v_rcp_f32_e32 v155, v155
	v_rcp_f32_e32 v186, v186
	s_nop 0
	s_nop 0
	v_cvt_pk_bf16_f32 v250, v155, v186
	v_mul_f32_e32 v155, 0xbfb8aa3b, v192
	v_mul_f32_e32 v186, 0xbfb8aa3b, v193
	v_exp_f32_e32 v155, v155
	v_exp_f32_e32 v186, v186
	v_add_f32_e32 v155, 1.0, v155
	v_add_f32_e32 v186, 1.0, v186
	v_rcp_f32_e32 v155, v155
	v_rcp_f32_e32 v186, v186
	s_nop 0
	s_nop 0
	v_cvt_pk_bf16_f32 v155, v155, v186
.LBB0_1201:
	s_andn2_b64 vcc, exec, s[14:15]
	s_mov_b64 s[14:15], 0
	s_cbranch_vccnz .LBB0_1205
	v_lshlrev_b32_e32 v114, 16, v236
	v_and_b32_e32 v115, 0xffff0000, v236
	v_lshlrev_b32_e32 v116, 16, v203
	s_nop 0
	v_and_b32_e32 v117, 0xffff0000, v203
	v_pk_fma_f32 v[110:111], v[110:111], v[116:117], v[114:115]
	v_lshlrev_b32_e32 v114, 16, v235
	s_nop 0
	v_and_b32_e32 v115, 0xffff0000, v235
	v_lshlrev_b32_e32 v116, 16, v204
	s_nop 0
	v_and_b32_e32 v117, 0xffff0000, v204
	v_pk_fma_f32 v[112:113], v[112:113], v[116:117], v[114:115]
	v_cvt_pk_bf16_f32 v236, v110, v111
	v_cvt_pk_bf16_f32 v235, v112, v113
	v_lshlrev_b32_e32 v110, 16, v234
	s_nop 0
	v_and_b32_e32 v111, 0xffff0000, v234
	v_lshlrev_b32_e32 v112, 16, v201
	s_nop 0
	v_and_b32_e32 v113, 0xffff0000, v201
	v_pk_fma_f32 v[106:107], v[106:107], v[112:113], v[110:111]
	v_lshlrev_b32_e32 v110, 16, v233
	s_nop 0
	v_and_b32_e32 v111, 0xffff0000, v233
	v_lshlrev_b32_e32 v112, 16, v202
	s_nop 0
	v_and_b32_e32 v113, 0xffff0000, v202
	v_pk_fma_f32 v[108:109], v[108:109], v[112:113], v[110:111]
	v_cvt_pk_bf16_f32 v234, v106, v107
	v_cvt_pk_bf16_f32 v233, v108, v109
	v_lshlrev_b32_e32 v106, 16, v232
	s_nop 0
	v_and_b32_e32 v107, 0xffff0000, v232
	v_lshlrev_b32_e32 v108, 16, v199
	s_nop 0
	v_and_b32_e32 v109, 0xffff0000, v199
	v_pk_fma_f32 v[102:103], v[102:103], v[108:109], v[106:107]
	v_lshlrev_b32_e32 v106, 16, v231
	s_nop 0
	v_and_b32_e32 v107, 0xffff0000, v231
	v_lshlrev_b32_e32 v108, 16, v200
	s_nop 0
	v_and_b32_e32 v109, 0xffff0000, v200
	v_pk_fma_f32 v[104:105], v[104:105], v[108:109], v[106:107]
	v_cvt_pk_bf16_f32 v232, v102, v103
	v_cvt_pk_bf16_f32 v231, v104, v105
	v_lshlrev_b32_e32 v102, 16, v230
	s_nop 0
	v_and_b32_e32 v103, 0xffff0000, v230
	v_lshlrev_b32_e32 v104, 16, v197
	s_nop 0
	v_and_b32_e32 v105, 0xffff0000, v197
	v_pk_fma_f32 v[98:99], v[98:99], v[104:105], v[102:103]
	v_lshlrev_b32_e32 v102, 16, v229
	s_nop 0
	v_and_b32_e32 v103, 0xffff0000, v229
	v_lshlrev_b32_e32 v104, 16, v198
	s_nop 0
	v_and_b32_e32 v105, 0xffff0000, v198
	v_pk_fma_f32 v[100:101], v[100:101], v[104:105], v[102:103]
	v_cvt_pk_bf16_f32 v230, v98, v99
	v_cvt_pk_bf16_f32 v229, v100, v101
	v_lshlrev_b32_e32 v98, 16, v228
	s_nop 0
	v_and_b32_e32 v99, 0xffff0000, v228
	v_lshlrev_b32_e32 v100, 16, v180
	s_nop 0
	v_and_b32_e32 v101, 0xffff0000, v180
	v_pk_fma_f32 v[94:95], v[94:95], v[100:101], v[98:99]
	v_lshlrev_b32_e32 v98, 16, v227
	s_nop 0
	v_and_b32_e32 v99, 0xffff0000, v227
	v_lshlrev_b32_e32 v100, 16, v181
	s_nop 0
	v_and_b32_e32 v101, 0xffff0000, v181
	v_pk_fma_f32 v[96:97], v[96:97], v[100:101], v[98:99]
	v_cvt_pk_bf16_f32 v228, v94, v95
	v_cvt_pk_bf16_f32 v227, v96, v97
	v_lshlrev_b32_e32 v94, 16, v226
	s_nop 0
	v_and_b32_e32 v95, 0xffff0000, v226
	v_lshlrev_b32_e32 v96, 16, v178
	s_nop 0
	v_and_b32_e32 v97, 0xffff0000, v178
	v_pk_fma_f32 v[90:91], v[90:91], v[96:97], v[94:95]
	v_lshlrev_b32_e32 v94, 16, v225
	s_nop 0
	v_and_b32_e32 v95, 0xffff0000, v225
	v_lshlrev_b32_e32 v96, 16, v179
	s_nop 0
	v_and_b32_e32 v97, 0xffff0000, v179
	v_pk_fma_f32 v[92:93], v[92:93], v[96:97], v[94:95]
	v_cvt_pk_bf16_f32 v226, v90, v91
	v_cvt_pk_bf16_f32 v225, v92, v93
	v_lshlrev_b32_e32 v90, 16, v224
	s_nop 0
	v_and_b32_e32 v91, 0xffff0000, v224
	v_lshlrev_b32_e32 v92, 16, v176
	s_nop 0
	v_and_b32_e32 v93, 0xffff0000, v176
	v_pk_fma_f32 v[86:87], v[86:87], v[92:93], v[90:91]
	v_lshlrev_b32_e32 v90, 16, v223
	s_nop 0
	v_and_b32_e32 v91, 0xffff0000, v223
	v_lshlrev_b32_e32 v92, 16, v177
	s_nop 0
	v_and_b32_e32 v93, 0xffff0000, v177
	v_pk_fma_f32 v[88:89], v[88:89], v[92:93], v[90:91]
	v_cvt_pk_bf16_f32 v224, v86, v87
	v_cvt_pk_bf16_f32 v223, v88, v89
	v_lshlrev_b32_e32 v86, 16, v222
	s_nop 0
	v_and_b32_e32 v87, 0xffff0000, v222
	v_lshlrev_b32_e32 v88, 16, v174
	s_nop 0
	v_and_b32_e32 v89, 0xffff0000, v174
	v_pk_fma_f32 v[82:83], v[82:83], v[88:89], v[86:87]
	v_lshlrev_b32_e32 v86, 16, v221
	s_nop 0
	v_and_b32_e32 v87, 0xffff0000, v221
	v_lshlrev_b32_e32 v88, 16, v175
	s_nop 0
	v_and_b32_e32 v89, 0xffff0000, v175
	v_pk_fma_f32 v[84:85], v[84:85], v[88:89], v[86:87]
	v_cvt_pk_bf16_f32 v222, v82, v83
	v_cvt_pk_bf16_f32 v221, v84, v85
	v_lshlrev_b32_e32 v82, 16, v220
	s_nop 0
	v_and_b32_e32 v83, 0xffff0000, v220
	v_lshlrev_b32_e32 v84, 16, v172
	s_nop 0
	v_and_b32_e32 v85, 0xffff0000, v172
	v_pk_fma_f32 v[78:79], v[78:79], v[84:85], v[82:83]
	v_lshlrev_b32_e32 v82, 16, v219
	s_nop 0
	v_and_b32_e32 v83, 0xffff0000, v219
	v_lshlrev_b32_e32 v84, 16, v173
	s_nop 0
	v_and_b32_e32 v85, 0xffff0000, v173
	v_pk_fma_f32 v[80:81], v[80:81], v[84:85], v[82:83]
	v_cvt_pk_bf16_f32 v220, v78, v79
	v_cvt_pk_bf16_f32 v219, v80, v81
	v_lshlrev_b32_e32 v78, 16, v218
	s_nop 0
	v_and_b32_e32 v79, 0xffff0000, v218
	v_lshlrev_b32_e32 v80, 16, v170
	s_nop 0
	v_and_b32_e32 v81, 0xffff0000, v170
	v_pk_fma_f32 v[74:75], v[74:75], v[80:81], v[78:79]
	v_lshlrev_b32_e32 v78, 16, v217
	s_nop 0
	v_and_b32_e32 v79, 0xffff0000, v217
	v_lshlrev_b32_e32 v80, 16, v171
	s_nop 0
	v_and_b32_e32 v81, 0xffff0000, v171
	v_pk_fma_f32 v[76:77], v[76:77], v[80:81], v[78:79]
	v_cvt_pk_bf16_f32 v218, v74, v75
	v_cvt_pk_bf16_f32 v217, v76, v77
	v_lshlrev_b32_e32 v74, 16, v216
	s_nop 0
	v_and_b32_e32 v75, 0xffff0000, v216
	v_lshlrev_b32_e32 v76, 16, v168
	s_nop 0
	v_and_b32_e32 v77, 0xffff0000, v168
	v_pk_fma_f32 v[70:71], v[70:71], v[76:77], v[74:75]
	v_lshlrev_b32_e32 v74, 16, v215
	s_nop 0
	v_and_b32_e32 v75, 0xffff0000, v215
	v_lshlrev_b32_e32 v76, 16, v169
	s_nop 0
	v_and_b32_e32 v77, 0xffff0000, v169
	v_pk_fma_f32 v[72:73], v[72:73], v[76:77], v[74:75]
	v_cvt_pk_bf16_f32 v216, v70, v71
	v_cvt_pk_bf16_f32 v215, v72, v73
	v_lshlrev_b32_e32 v70, 16, v214
	s_nop 0
	v_and_b32_e32 v71, 0xffff0000, v214
	v_lshlrev_b32_e32 v72, 16, v166
	s_nop 0
	v_and_b32_e32 v73, 0xffff0000, v166
	v_pk_fma_f32 v[66:67], v[66:67], v[72:73], v[70:71]
	v_lshlrev_b32_e32 v70, 16, v213
	s_nop 0
	v_and_b32_e32 v71, 0xffff0000, v213
	v_lshlrev_b32_e32 v72, 16, v167
	s_nop 0
	v_and_b32_e32 v73, 0xffff0000, v167
	v_pk_fma_f32 v[68:69], v[68:69], v[72:73], v[70:71]
	v_cvt_pk_bf16_f32 v214, v66, v67
	v_cvt_pk_bf16_f32 v213, v68, v69
	v_lshlrev_b32_e32 v66, 16, v212
	s_nop 0
	v_and_b32_e32 v67, 0xffff0000, v212
	v_lshlrev_b32_e32 v68, 16, v160
	s_nop 0
	v_and_b32_e32 v69, 0xffff0000, v160
	v_pk_fma_f32 v[62:63], v[62:63], v[68:69], v[66:67]
	v_lshlrev_b32_e32 v66, 16, v211
	s_nop 0
	v_and_b32_e32 v67, 0xffff0000, v211
	v_lshlrev_b32_e32 v68, 16, v161
	s_nop 0
	v_and_b32_e32 v69, 0xffff0000, v161
	v_pk_fma_f32 v[64:65], v[64:65], v[68:69], v[66:67]
	v_cvt_pk_bf16_f32 v212, v62, v63
	v_cvt_pk_bf16_f32 v211, v64, v65
	v_lshlrev_b32_e32 v62, 16, v210
	s_nop 0
	v_and_b32_e32 v63, 0xffff0000, v210
	v_lshlrev_b32_e32 v64, 16, v158
	s_nop 0
	v_and_b32_e32 v65, 0xffff0000, v158
	v_pk_fma_f32 v[58:59], v[58:59], v[64:65], v[62:63]
	v_lshlrev_b32_e32 v62, 16, v209
	s_nop 0
	v_and_b32_e32 v63, 0xffff0000, v209
	v_lshlrev_b32_e32 v64, 16, v159
	s_nop 0
	v_and_b32_e32 v65, 0xffff0000, v159
	v_pk_fma_f32 v[60:61], v[60:61], v[64:65], v[62:63]
	v_cvt_pk_bf16_f32 v210, v58, v59
	v_cvt_pk_bf16_f32 v209, v60, v61
	v_lshlrev_b32_e32 v58, 16, v208
	s_nop 0
	v_and_b32_e32 v59, 0xffff0000, v208
	v_lshlrev_b32_e32 v60, 16, v156
	s_nop 0
	v_and_b32_e32 v61, 0xffff0000, v156
	v_pk_fma_f32 v[54:55], v[54:55], v[60:61], v[58:59]
	v_lshlrev_b32_e32 v58, 16, v207
	s_nop 0
	v_and_b32_e32 v59, 0xffff0000, v207
	v_lshlrev_b32_e32 v60, 16, v157
	s_nop 0
	v_and_b32_e32 v61, 0xffff0000, v157
	v_pk_fma_f32 v[56:57], v[56:57], v[60:61], v[58:59]
	v_cvt_pk_bf16_f32 v208, v54, v55
	v_cvt_pk_bf16_f32 v207, v56, v57
	v_lshlrev_b32_e32 v54, 16, v206
	s_nop 0
	v_and_b32_e32 v55, 0xffff0000, v206
	v_lshlrev_b32_e32 v56, 16, v154
	s_nop 0
	v_and_b32_e32 v57, 0xffff0000, v154
	v_pk_fma_f32 v[50:51], v[50:51], v[56:57], v[54:55]
	v_lshlrev_b32_e32 v54, 16, v205
	s_nop 0
	v_and_b32_e32 v55, 0xffff0000, v205
	v_lshlrev_b32_e32 v56, 16, v195
	s_nop 0
	v_and_b32_e32 v57, 0xffff0000, v195
	v_pk_fma_f32 v[52:53], v[52:53], v[56:57], v[54:55]
	v_cvt_pk_bf16_f32 v206, v50, v51
	v_cvt_pk_bf16_f32 v205, v52, v53
	s_cmp_lg_u32 s38, 1
	s_cbranch_scc1 .LBB0_1206
	v_readlane_b32 s98, v252, 2
	v_readlane_b32 s99, v252, 3
	v_readlane_b32 vcc_lo, v253, 30
	s_lshl_b32 vcc_lo, vcc_lo, 7
	s_lshr_b32 vcc_hi, s39, 3
	s_add_i32 vcc_lo, vcc_lo, vcc_hi
	s_lshl_b32 vcc_lo, vcc_lo, 6
	s_and_b32 vcc_hi, s39, 7
	s_add_i32 vcc_lo, vcc_lo, vcc_hi
	s_lshl_b32 vcc_lo, vcc_lo, 2
	v_mov_b32_e32 v162, vcc_lo

.Lm4_ok:
	s_nop 0
	v_mov_b64_e32 v[162:163], 0x200
	s_and_b32 s14, s41, 0x7fffff8
	s_add_i32 s14, s14, s18
	s_nop 0
	v_lshl_or_b32 v50, s14, 5, v1
	v_readlane_b32 s52, v253, 32
	v_ashrrev_i32_e32 v51, 31, v50
	s_nop 0
	v_readlane_b32 s53, v253, 33
	s_lshl_b32 s14, s39, 5
	s_nop 0
	s_and_b32 s14, s14, 0xffffff00
	v_lshl_add_u64 v[50:51], v[50:51], 2, s[52:53]
	global_load_dword v88, v[50:51], off
	global_load_dword v89, v[50:51], off offset:64
	global_load_dword v90, v[50:51], off offset:512
	global_load_dword v91, v[50:51], off offset:576
	v_add_u32_e32 v50, s14, v135
	s_lshl_b32 s14, s39, 7
	s_and_b32 s17, s14, 0x380
	s_lshl_b32 s14, s17, 1
	s_add_u32 s14, s22, s14
	v_ashrrev_i32_e32 v51, 31, v50
	s_addc_u32 s15, s23, 0
	v_lshlrev_b64 v[80:81], 11, v[50:51]
	v_lshl_add_u64 v[52:53], s[14:15], 0, v[80:81]
	v_mov_b32_e32 v139, v0
	s_nop 0
	v_lshl_add_u64 v[52:53], v[52:53], 0, v[138:139]
	global_load_dwordx4 v[92:95], v[52:53], off sc1
	global_load_dwordx4 v[74:77], v[52:53], off offset:64 sc1
	v_or_b32_e32 v52, 16, v50
	v_ashrrev_i32_e32 v53, 31, v52
	v_lshlrev_b64 v[84:85], 11, v[52:53]
	v_lshl_add_u64 v[52:53], s[14:15], 0, v[84:85]
	v_lshl_add_u64 v[52:53], v[52:53], 0, v[138:139]
	global_load_dwordx4 v[70:73], v[52:53], off sc1
	global_load_dwordx4 v[66:69], v[52:53], off offset:64 sc1
	v_add_u32_e32 v52, 0x80, v50
	v_ashrrev_i32_e32 v53, 31, v52
	s_nop 0
	v_lshlrev_b64 v[82:83], 11, v[52:53]
	v_lshl_add_u64 v[52:53], s[14:15], 0, v[82:83]
	v_lshl_add_u64 v[52:53], v[52:53], 0, v[138:139]
	global_load_dwordx4 v[62:65], v[52:53], off sc1
	global_load_dwordx4 v[58:61], v[52:53], off offset:64 sc1
	v_add_u32_e32 v50, 0x90, v50
	v_ashrrev_i32_e32 v51, 31, v50
	s_nop 0
	v_lshlrev_b64 v[78:79], 11, v[50:51]
	v_lshl_add_u64 v[50:51], s[14:15], 0, v[78:79]
	v_lshl_add_u64 v[50:51], v[50:51], 0, v[138:139]
	global_load_dwordx4 v[54:57], v[50:51], off sc1
	s_nop 0
	s_nop 0
	global_load_dwordx4 v[50:53], v[50:51], off offset:64 sc1
	v_readlane_b32 s60, v253, 40
	v_readlane_b32 s61, v253, 41
	v_or_b32_e32 v96, s17, v140
	s_nop 0
	v_and_b32_e32 v97, 0xffff0000, v236
	v_lshl_add_u64 v[86:87], s[60:61], 0, v[80:81]
	v_lshlrev_b32_e32 v80, 1, v96
	v_lshlrev_b32_e32 v96, 16, v236
	v_mov_b32_e32 v81, v0
	s_nop 0
	v_lshl_add_u64 v[86:87], v[86:87], 0, v[80:81]
	s_mov_b64 s[14:15], -1
	v_mov_b32_e32 v236, 0
	v_readlane_b32 s54, v253, 34
	v_readlane_b32 s55, v253, 35
	v_readlane_b32 s56, v253, 36
	v_readlane_b32 s57, v253, 37
	v_readlane_b32 s58, v253, 38
	v_readlane_b32 s59, v253, 39
	v_readlane_b32 s62, v253, 42
	v_readlane_b32 s63, v253, 43
	v_readlane_b32 s64, v253, 44
	v_readlane_b32 s65, v253, 45
	v_readlane_b32 s66, v253, 46
	v_readlane_b32 s67, v253, 47
	s_waitcnt vmcnt(0)
	v_lshlrev_b32_e32 v98, 16, v92
	v_and_b32_e32 v99, 0xffff0000, v92
	v_pk_add_f32 v[96:97], v[96:97], v[98:99]
	v_lshlrev_b32_e32 v98, 16, v93
	s_nop 0
	v_cvt_pk_bf16_f32 v92, v96, v97
	v_lshlrev_b32_e32 v96, 16, v235
	s_nop 0
	v_and_b32_e32 v97, 0xffff0000, v235
	v_and_b32_e32 v99, 0xffff0000, v93
	v_pk_add_f32 v[96:97], v[96:97], v[98:99]
	v_lshlrev_b32_e32 v98, 16, v94
	s_nop 0
	v_cvt_pk_bf16_f32 v93, v96, v97
	v_lshlrev_b32_e32 v96, 16, v234
	s_nop 0
	v_and_b32_e32 v97, 0xffff0000, v234
	v_and_b32_e32 v99, 0xffff0000, v94
	v_pk_add_f32 v[96:97], v[96:97], v[98:99]
	v_lshlrev_b32_e32 v98, 16, v95
	s_nop 0
	v_cvt_pk_bf16_f32 v94, v96, v97
	v_lshlrev_b32_e32 v96, 16, v233
	s_nop 0
	v_and_b32_e32 v97, 0xffff0000, v233
	v_and_b32_e32 v99, 0xffff0000, v95
	v_pk_add_f32 v[96:97], v[96:97], v[98:99]
	v_mov_b32_e32 v235, 0
	s_nop 0
	v_cvt_pk_bf16_f32 v95, v96, v97
	global_store_dwordx4 v[86:87], v[92:95], off
	v_mov_b32_e32 v233, 0
	v_mov_b32_e32 v234, 0
	v_lshlrev_b32_e32 v92, 16, v232
	s_nop 0
	v_and_b32_e32 v93, 0xffff0000, v232
	v_lshlrev_b32_e32 v94, 16, v74
	s_nop 0
	v_and_b32_e32 v95, 0xffff0000, v74
	v_pk_add_f32 v[92:93], v[92:93], v[94:95]
	v_lshlrev_b32_e32 v94, 16, v75
	s_nop 0
	v_cvt_pk_bf16_f32 v74, v92, v93
	v_lshlrev_b32_e32 v92, 16, v231
	s_nop 0
	v_and_b32_e32 v93, 0xffff0000, v231
	v_and_b32_e32 v95, 0xffff0000, v75
	v_pk_add_f32 v[92:93], v[92:93], v[94:95]
	v_lshlrev_b32_e32 v94, 16, v76
	s_nop 0
	v_cvt_pk_bf16_f32 v75, v92, v93
	v_lshlrev_b32_e32 v92, 16, v230
	s_nop 0
	v_and_b32_e32 v93, 0xffff0000, v230
	v_and_b32_e32 v95, 0xffff0000, v76
	v_pk_add_f32 v[92:93], v[92:93], v[94:95]
	v_lshlrev_b32_e32 v94, 16, v77
	s_nop 0
	v_cvt_pk_bf16_f32 v76, v92, v93
	v_lshlrev_b32_e32 v92, 16, v229
	s_nop 0
	v_and_b32_e32 v93, 0xffff0000, v229
	v_and_b32_e32 v95, 0xffff0000, v77
	v_pk_add_f32 v[92:93], v[92:93], v[94:95]
	v_mov_b32_e32 v231, 0
	s_nop 0
	v_cvt_pk_bf16_f32 v77, v92, v93
	global_store_dwordx4 v[86:87], v[74:77], off offset:64
	v_mov_b32_e32 v232, 0
	v_mov_b32_e32 v229, 0
	v_lshl_add_u64 v[74:75], s[60:61], 0, v[84:85]
	v_lshlrev_b32_e32 v76, 16, v228
	s_nop 0
	v_and_b32_e32 v77, 0xffff0000, v228
	v_lshlrev_b32_e32 v84, 16, v70
	s_nop 0
	v_and_b32_e32 v85, 0xffff0000, v70
	v_pk_add_f32 v[76:77], v[76:77], v[84:85]
	v_lshlrev_b32_e32 v84, 16, v71
	s_nop 0
	v_cvt_pk_bf16_f32 v70, v76, v77
	v_lshlrev_b32_e32 v76, 16, v227
	s_nop 0
	v_and_b32_e32 v77, 0xffff0000, v227
	v_and_b32_e32 v85, 0xffff0000, v71
	v_pk_add_f32 v[76:77], v[76:77], v[84:85]
	v_lshlrev_b32_e32 v84, 16, v72
	s_nop 0
	v_cvt_pk_bf16_f32 v71, v76, v77
	v_lshlrev_b32_e32 v76, 16, v226
	s_nop 0
	v_and_b32_e32 v77, 0xffff0000, v226
	v_and_b32_e32 v85, 0xffff0000, v72
	v_pk_add_f32 v[76:77], v[76:77], v[84:85]
	v_lshlrev_b32_e32 v84, 16, v73
	s_nop 0
	v_cvt_pk_bf16_f32 v72, v76, v77
	v_lshlrev_b32_e32 v76, 16, v225
	s_nop 0
	v_and_b32_e32 v77, 0xffff0000, v225
	v_and_b32_e32 v85, 0xffff0000, v73
	v_pk_add_f32 v[76:77], v[76:77], v[84:85]
	v_lshl_add_u64 v[74:75], v[74:75], 0, v[80:81]
	v_cvt_pk_bf16_f32 v73, v76, v77
	global_store_dwordx4 v[74:75], v[70:73], off
	v_mov_b32_e32 v230, 0
	v_mov_b32_e32 v227, 0
	v_lshlrev_b32_e32 v70, 16, v224
	s_nop 0
	v_and_b32_e32 v71, 0xffff0000, v224
	v_lshlrev_b32_e32 v72, 16, v66
	s_nop 0
	v_and_b32_e32 v73, 0xffff0000, v66
	v_pk_add_f32 v[70:71], v[70:71], v[72:73]
	v_lshlrev_b32_e32 v72, 16, v67
	s_nop 0
	v_cvt_pk_bf16_f32 v66, v70, v71
	v_lshlrev_b32_e32 v70, 16, v223
	s_nop 0
	v_and_b32_e32 v71, 0xffff0000, v223
	v_and_b32_e32 v73, 0xffff0000, v67
	v_pk_add_f32 v[70:71], v[70:71], v[72:73]
	v_lshlrev_b32_e32 v72, 16, v68
	s_nop 0
	v_cvt_pk_bf16_f32 v67, v70, v71
	v_lshlrev_b32_e32 v70, 16, v222
	s_nop 0
	v_and_b32_e32 v71, 0xffff0000, v222
	v_and_b32_e32 v73, 0xffff0000, v68
	v_pk_add_f32 v[70:71], v[70:71], v[72:73]
	v_lshlrev_b32_e32 v72, 16, v69
	s_nop 0
	v_cvt_pk_bf16_f32 v68, v70, v71
	v_lshlrev_b32_e32 v70, 16, v221
	s_nop 0
	v_and_b32_e32 v71, 0xffff0000, v221
	v_and_b32_e32 v73, 0xffff0000, v69
	v_pk_add_f32 v[70:71], v[70:71], v[72:73]
	v_mov_b32_e32 v228, 0
	s_nop 0
	v_cvt_pk_bf16_f32 v69, v70, v71
	global_store_dwordx4 v[74:75], v[66:69], off offset:64
	v_lshlrev_b32_e32 v70, 16, v62
	s_nop 0
	v_and_b32_e32 v71, 0xffff0000, v62
	v_lshlrev_b32_e32 v68, 16, v220
	s_nop 0
	v_and_b32_e32 v69, 0xffff0000, v220
	v_pk_add_f32 v[68:69], v[68:69], v[70:71]
	v_lshlrev_b32_e32 v70, 16, v63
	s_nop 0
	v_cvt_pk_bf16_f32 v62, v68, v69
	v_lshlrev_b32_e32 v68, 16, v219
	s_nop 0
	v_and_b32_e32 v69, 0xffff0000, v219
	v_and_b32_e32 v71, 0xffff0000, v63
	v_pk_add_f32 v[68:69], v[68:69], v[70:71]
	v_lshlrev_b32_e32 v70, 16, v64
	s_nop 0
	v_cvt_pk_bf16_f32 v63, v68, v69
	v_lshlrev_b32_e32 v68, 16, v218
	s_nop 0
	v_and_b32_e32 v69, 0xffff0000, v218
	v_and_b32_e32 v71, 0xffff0000, v64
	v_pk_add_f32 v[68:69], v[68:69], v[70:71]
	v_lshlrev_b32_e32 v70, 16, v65
	s_nop 0
	v_cvt_pk_bf16_f32 v64, v68, v69
	v_lshlrev_b32_e32 v68, 16, v217
	s_nop 0
	v_and_b32_e32 v69, 0xffff0000, v217
	v_and_b32_e32 v71, 0xffff0000, v65
	v_lshl_add_u64 v[66:67], s[60:61], 0, v[82:83]
	v_pk_add_f32 v[68:69], v[68:69], v[70:71]
	v_lshl_add_u64 v[66:67], v[66:67], 0, v[80:81]
	v_cvt_pk_bf16_f32 v65, v68, v69
	global_store_dwordx4 v[66:67], v[62:65], off
	v_mov_b32_e32 v225, 0
	v_mov_b32_e32 v226, 0
	v_lshlrev_b32_e32 v62, 16, v216
	s_nop 0
	v_and_b32_e32 v63, 0xffff0000, v216
	v_lshlrev_b32_e32 v64, 16, v58
	s_nop 0
	v_and_b32_e32 v65, 0xffff0000, v58
	v_pk_add_f32 v[62:63], v[62:63], v[64:65]
	v_lshlrev_b32_e32 v64, 16, v59
	s_nop 0
	v_cvt_pk_bf16_f32 v58, v62, v63
	v_lshlrev_b32_e32 v62, 16, v215
	s_nop 0
	v_and_b32_e32 v63, 0xffff0000, v215
	v_and_b32_e32 v65, 0xffff0000, v59
	v_pk_add_f32 v[62:63], v[62:63], v[64:65]
	v_lshlrev_b32_e32 v64, 16, v60
	s_nop 0
	v_cvt_pk_bf16_f32 v59, v62, v63
	v_lshlrev_b32_e32 v62, 16, v214
	s_nop 0
	v_and_b32_e32 v63, 0xffff0000, v214
	v_and_b32_e32 v65, 0xffff0000, v60
	v_pk_add_f32 v[62:63], v[62:63], v[64:65]
	v_lshlrev_b32_e32 v64, 16, v61
	s_nop 0
	v_cvt_pk_bf16_f32 v60, v62, v63
	v_lshlrev_b32_e32 v62, 16, v213
	s_nop 0
	v_and_b32_e32 v63, 0xffff0000, v213
	v_and_b32_e32 v65, 0xffff0000, v61
	v_pk_add_f32 v[62:63], v[62:63], v[64:65]
	v_mov_b32_e32 v223, 0
	s_nop 0
	v_cvt_pk_bf16_f32 v61, v62, v63
	global_store_dwordx4 v[66:67], v[58:61], off offset:64
	v_lshlrev_b32_e32 v62, 16, v54
	s_nop 0
	v_and_b32_e32 v63, 0xffff0000, v54
	v_lshlrev_b32_e32 v60, 16, v212
	s_nop 0
	v_and_b32_e32 v61, 0xffff0000, v212
	v_pk_add_f32 v[60:61], v[60:61], v[62:63]
	v_lshlrev_b32_e32 v62, 16, v55
	s_nop 0
	v_cvt_pk_bf16_f32 v54, v60, v61
	v_lshlrev_b32_e32 v60, 16, v211
	s_nop 0
	v_and_b32_e32 v61, 0xffff0000, v211
	v_and_b32_e32 v63, 0xffff0000, v55
	v_pk_add_f32 v[60:61], v[60:61], v[62:63]
	v_lshlrev_b32_e32 v62, 16, v56
	s_nop 0
	v_cvt_pk_bf16_f32 v55, v60, v61
	v_lshlrev_b32_e32 v60, 16, v210
	s_nop 0
	v_and_b32_e32 v61, 0xffff0000, v210
	v_and_b32_e32 v63, 0xffff0000, v56
	v_pk_add_f32 v[60:61], v[60:61], v[62:63]
	v_lshlrev_b32_e32 v62, 16, v57
	s_nop 0
	v_cvt_pk_bf16_f32 v56, v60, v61
	v_lshlrev_b32_e32 v60, 16, v209
	s_nop 0
	v_and_b32_e32 v61, 0xffff0000, v209
	v_and_b32_e32 v63, 0xffff0000, v57
	v_lshl_add_u64 v[58:59], s[60:61], 0, v[78:79]
	v_pk_add_f32 v[60:61], v[60:61], v[62:63]
	v_lshl_add_u64 v[58:59], v[58:59], 0, v[80:81]
	v_cvt_pk_bf16_f32 v57, v60, v61
	global_store_dwordx4 v[58:59], v[54:57], off
	v_mov_b32_e32 v224, 0
	v_mov_b32_e32 v221, 0
	v_lshlrev_b32_e32 v54, 16, v208
	s_nop 0
	v_and_b32_e32 v55, 0xffff0000, v208
	v_lshlrev_b32_e32 v56, 16, v50
	s_nop 0
	v_and_b32_e32 v57, 0xffff0000, v50
	v_pk_add_f32 v[54:55], v[54:55], v[56:57]
	v_lshlrev_b32_e32 v56, 16, v51
	s_nop 0
	v_cvt_pk_bf16_f32 v50, v54, v55
	v_lshlrev_b32_e32 v54, 16, v207
	s_nop 0
	v_and_b32_e32 v55, 0xffff0000, v207
	v_and_b32_e32 v57, 0xffff0000, v51
	v_pk_add_f32 v[54:55], v[54:55], v[56:57]
	v_lshlrev_b32_e32 v56, 16, v52
	s_nop 0
	v_cvt_pk_bf16_f32 v51, v54, v55
	v_lshlrev_b32_e32 v54, 16, v206
	s_nop 0
	v_and_b32_e32 v55, 0xffff0000, v206
	v_and_b32_e32 v57, 0xffff0000, v52
	v_pk_add_f32 v[54:55], v[54:55], v[56:57]
	v_lshlrev_b32_e32 v56, 16, v53
	s_nop 0
	v_cvt_pk_bf16_f32 v52, v54, v55
	v_lshlrev_b32_e32 v54, 16, v205
	s_nop 0
	v_and_b32_e32 v55, 0xffff0000, v205
	v_and_b32_e32 v57, 0xffff0000, v53
	v_pk_add_f32 v[54:55], v[54:55], v[56:57]
	v_mov_b32_e32 v222, 0
	s_nop 0
	v_cvt_pk_bf16_f32 v53, v54, v55
	v_mov_b32_e32 v219, 0
	v_mov_b32_e32 v220, 0
	v_mov_b32_e32 v217, 0
	v_mov_b32_e32 v218, 0
	v_mov_b32_e32 v215, 0
	v_mov_b32_e32 v216, 0
	v_mov_b32_e32 v213, 0
	v_mov_b32_e32 v214, 0
	v_mov_b32_e32 v211, 0
	v_mov_b32_e32 v212, 0
	v_mov_b32_e32 v209, 0
	v_mov_b32_e32 v210, 0
	v_mov_b32_e32 v207, 0
	v_mov_b32_e32 v208, 0
	v_mov_b32_e32 v205, 0
	v_mov_b32_e32 v206, 0
	global_store_dwordx4 v[58:59], v[50:53], off offset:64
	ds_write2_b32 v137, v88, v89 offset1:16
	ds_write2_b32 v137, v90, v91 offset0:128 offset1:144
	s_branch .LBB0_1206

.LBB0_1207:
	s_andn2_b64 vcc, exec, s[12:13]
	s_cbranch_vccnz .LBB0_1171
	s_mov_b32 s36, 0
	s_mov_b64 s[6:7], s[4:5]
	s_mov_b32 s37, s40
	s_mov_b32 s38, s42
	s_mov_b32 s39, s41
	s_branch .LBB0_1171
	s_nop 0
